# S30: S27 + h3 final-stage token sums: 48 serial ds_bpermute butterflies -> DPP / permlane16/32 swaps, lgkmcnt recounted
# speedup vs baseline: 1.0011x; 1.0011x over previous
; __device__ __forceinline__ void hg_h3_unit(Frame& F, int l, int unit) {
;     ...
;     { const int ln = t_l & 63;
;       const float nw0 = F.hgrn_norm_w[l * 128 + ln], nw1 = F.hgrn_norm_w[l * 128 + 64 + ln];
;       bf16* MIX = (bf16*)(F.ws + WS_MIX);
;       float v0[8], v1[8], ss[8];
; #pragma unroll
;       for (int tt = 0; tt < 8; ++tt) { const int t = F.wave * 8 + tt; v0[tt] = OS[t * 128 + ln]; v1[tt] = OS[t * 128 + 64 + ln]; ss[tt] = v0[tt] * v0[tt] + v1[tt] * v1[tt]; }
; #pragma unroll
;       for (int o = 1; o < 64; o <<= 1)
; #pragma unroll
;           for (int tt = 0; tt < 8; ++tt) ss[tt] += __shfl_xor(ss[tt], o);
.LBB0_909:
	v_readlane_b32 s76, v249, 12
	v_or_b32_e32 v146, s19, v142
	v_readlane_b32 s82, v249, 18
	v_readlane_b32 s83, v249, 19
	v_and_b32_e32 v27, 64, v185
	v_add_u32_e32 v27, 64, v27
	v_lshl_add_u64 v[2:3], v[146:147], 2, s[82:83]
	global_load_dword v18, v[2:3], off
	global_load_dword v1, v[2:3], off offset:256
	v_lshl_add_u32 v2, v142, 2, s56
	ds_read2st64_b32 v[16:17], v2 offset1:1
	ds_read2st64_b32 v[14:15], v2 offset0:2 offset1:3
	ds_read2st64_b32 v[12:13], v2 offset0:4 offset1:5
	ds_read2st64_b32 v[10:11], v2 offset0:6 offset1:7
	v_xor_b32_e32 v28, 1, v185
	v_cmp_lt_i32_e32 vcc, v28, v27
	s_waitcnt lgkmcnt(3)
	v_mul_f32_e32 v19, v17, v17
	v_fmac_f32_e32 v19, v16, v16
	v_cndmask_b32_e32 v28, v185, v28, vcc
	v_lshlrev_b32_e32 v28, 2, v28
	s_nop 1
	v_mov_b32_dpp v29, v19 quad_perm:[1,0,3,2] row_mask:0xf bank_mask:0xf
	s_waitcnt lgkmcnt(2)
	v_mul_f32_e32 v20, v15, v15
	v_fmac_f32_e32 v20, v14, v14
	s_waitcnt lgkmcnt(1)
	v_mul_f32_e32 v21, v13, v13
	v_fmac_f32_e32 v21, v12, v12
	s_waitcnt lgkmcnt(0)
	v_add_f32_e32 v19, v19, v29
	s_nop 1
	v_mov_b32_dpp v29, v20 quad_perm:[1,0,3,2] row_mask:0xf bank_mask:0xf
	v_mul_f32_e32 v22, v11, v11
	ds_read2st64_b32 v[8:9], v2 offset0:8 offset1:9
	ds_read2st64_b32 v[6:7], v2 offset0:10 offset1:11
	ds_read2st64_b32 v[4:5], v2 offset0:12 offset1:13
	s_waitcnt lgkmcnt(3)
	v_add_f32_e32 v20, v20, v29
	s_nop 1
	v_mov_b32_dpp v29, v21 quad_perm:[1,0,3,2] row_mask:0xf bank_mask:0xf
	v_fmac_f32_e32 v22, v10, v10
	s_waitcnt lgkmcnt(2)
	v_mul_f32_e32 v23, v9, v9
	v_fmac_f32_e32 v23, v8, v8
	s_waitcnt lgkmcnt(1)
	v_mul_f32_e32 v24, v7, v7
	s_waitcnt lgkmcnt(0)
	v_add_f32_e32 v21, v21, v29
	s_nop 1
	v_mov_b32_dpp v29, v22 quad_perm:[1,0,3,2] row_mask:0xf bank_mask:0xf
	ds_read2st64_b32 v[2:3], v2 offset0:14 offset1:15
	v_fmac_f32_e32 v24, v6, v6
	v_mul_f32_e32 v25, v5, v5
	v_fmac_f32_e32 v25, v4, v4
	s_waitcnt lgkmcnt(1)
	v_add_f32_e32 v22, v22, v29
	s_nop 1
	v_mov_b32_dpp v29, v23 quad_perm:[1,0,3,2] row_mask:0xf bank_mask:0xf
	s_waitcnt lgkmcnt(0)
	v_mul_f32_e32 v26, v3, v3
	v_fmac_f32_e32 v26, v2, v2
	s_mov_b32 s12, 0xf800000
	s_add_i32 s6, s63, s57
	s_waitcnt lgkmcnt(0)
	v_add_f32_e32 v23, v23, v29
	s_nop 1
	v_mov_b32_dpp v29, v24 quad_perm:[1,0,3,2] row_mask:0xf bank_mask:0xf
	s_ashr_i32 s7, s6, 31
	v_readlane_b32 s8, v253, 37
	v_readlane_b32 s9, v253, 38
	v_readlane_b32 s10, v253, 39
	s_waitcnt lgkmcnt(0)
	v_add_f32_e32 v24, v24, v29
	s_nop 1
	v_mov_b32_dpp v29, v25 quad_perm:[1,0,3,2] row_mask:0xf bank_mask:0xf
	s_nop 1
	v_mov_b32_dpp v28, v26 quad_perm:[1,0,3,2] row_mask:0xf bank_mask:0xf
	v_lshlrev_b32_e32 v146, 1, v142
	s_mov_b64 s[14:15], 0x3a400c00
	s_mov_b32 s10, 0x3a400000
	s_waitcnt lgkmcnt(0)
	v_add_f32_e32 v25, v25, v29
	s_waitcnt lgkmcnt(0)
	v_add_f32_e32 v26, v26, v28
	v_xor_b32_e32 v28, 2, v185
	v_cmp_lt_i32_e32 vcc, v28, v27
	s_mov_b32 s63, 0x42800000
	v_readlane_b32 s77, v249, 13
	v_cndmask_b32_e32 v28, v185, v28, vcc
	v_lshlrev_b32_e32 v28, 2, v28
	s_nop 1
	v_mov_b32_dpp v29, v19 quad_perm:[2,3,0,1] row_mask:0xf bank_mask:0xf
	v_readlane_b32 s78, v249, 14
	v_readlane_b32 s79, v249, 15
	v_readlane_b32 s80, v249, 16
	v_readlane_b32 s81, v249, 17
	s_waitcnt lgkmcnt(0)
	v_add_f32_e32 v19, v19, v29
	s_nop 1
	v_mov_b32_dpp v29, v20 quad_perm:[2,3,0,1] row_mask:0xf bank_mask:0xf
	v_readlane_b32 s84, v249, 20
	v_readlane_b32 s85, v249, 21
	v_readlane_b32 s86, v249, 22
	v_readlane_b32 s87, v249, 23
	s_waitcnt lgkmcnt(0)
	v_add_f32_e32 v20, v20, v29
	s_nop 1
	v_mov_b32_dpp v29, v21 quad_perm:[2,3,0,1] row_mask:0xf bank_mask:0xf
	v_readlane_b32 s88, v249, 24
	v_readlane_b32 s89, v249, 25
	v_readlane_b32 s90, v249, 26
	v_readlane_b32 s91, v249, 27
	s_waitcnt lgkmcnt(0)
	v_add_f32_e32 v21, v21, v29
	s_nop 1
	v_mov_b32_dpp v29, v22 quad_perm:[2,3,0,1] row_mask:0xf bank_mask:0xf
	v_readlane_b32 s11, v253, 40
	s_waitcnt lgkmcnt(0)
	v_add_f32_e32 v22, v22, v29
	s_nop 1
	v_mov_b32_dpp v29, v23 quad_perm:[2,3,0,1] row_mask:0xf bank_mask:0xf
	s_waitcnt lgkmcnt(0)
	v_add_f32_e32 v23, v23, v29
	s_nop 1
	v_mov_b32_dpp v29, v24 quad_perm:[2,3,0,1] row_mask:0xf bank_mask:0xf
	s_waitcnt lgkmcnt(0)
	v_add_f32_e32 v24, v24, v29
	s_nop 1
	v_mov_b32_dpp v29, v25 quad_perm:[2,3,0,1] row_mask:0xf bank_mask:0xf
	s_nop 1
	v_mov_b32_dpp v28, v26 quad_perm:[2,3,0,1] row_mask:0xf bank_mask:0xf
	s_waitcnt lgkmcnt(0)
	v_add_f32_e32 v25, v25, v29
	s_waitcnt lgkmcnt(0)
	v_add_f32_e32 v26, v26, v28
	v_xor_b32_e32 v28, 4, v185
	v_cmp_lt_i32_e32 vcc, v28, v27
	s_nop 1
	v_cndmask_b32_e32 v28, v185, v28, vcc
	v_lshlrev_b32_e32 v28, 2, v28
	s_nop 1
	v_mov_b32_dpp v29, v19 row_half_mirror row_mask:0xf bank_mask:0xf
	s_waitcnt lgkmcnt(0)
	v_add_f32_e32 v19, v19, v29
	s_nop 1
	v_mov_b32_dpp v29, v20 row_half_mirror row_mask:0xf bank_mask:0xf
	s_waitcnt lgkmcnt(0)
	v_add_f32_e32 v20, v20, v29
	s_nop 1
	v_mov_b32_dpp v29, v21 row_half_mirror row_mask:0xf bank_mask:0xf
	s_waitcnt lgkmcnt(0)
	v_add_f32_e32 v21, v21, v29
	s_nop 1
	v_mov_b32_dpp v29, v22 row_half_mirror row_mask:0xf bank_mask:0xf
	s_waitcnt lgkmcnt(0)
	v_add_f32_e32 v22, v22, v29
	s_nop 1
	v_mov_b32_dpp v29, v23 row_half_mirror row_mask:0xf bank_mask:0xf
	s_waitcnt lgkmcnt(0)
	v_add_f32_e32 v23, v23, v29
	s_nop 1
	v_mov_b32_dpp v29, v24 row_half_mirror row_mask:0xf bank_mask:0xf
	s_waitcnt lgkmcnt(0)
	v_add_f32_e32 v24, v24, v29
	s_nop 1
	v_mov_b32_dpp v29, v25 row_half_mirror row_mask:0xf bank_mask:0xf
	s_nop 1
	v_mov_b32_dpp v28, v26 row_half_mirror row_mask:0xf bank_mask:0xf
	s_waitcnt lgkmcnt(0)
	v_add_f32_e32 v25, v25, v29
	s_waitcnt lgkmcnt(0)
; __device__ __forceinline__ unsigned f2bf(float f) { unsigned u = __builtin_bit_cast(unsigned, f); return (u + 0x7fffu + ((u >> 16) & 1u)) >> 16; }
; __device__ __forceinline__ void hg_h3_unit(Frame& F, int l, int unit) {
;     ...
;       for (int o = 1; o < 64; o <<= 1)
; #pragma unroll
;           for (int tt = 0; tt < 8; ++tt) ss[tt] += __shfl_xor(ss[tt], o);
; #pragma unroll
;       for (int tt = 0; tt < 8; ++tt) { const int t = F.wave * 8 + tt; const float rs = 1.0f / sqrtf(ss[tt] * (1.0f / 128.0f) + LN_EPS);
;           const size_t row = (size_t)(base0 + t); const float g0 = bflo(gin0[tt]), g1 = bflo(gin1[tt]);
;           bf16* mp = MIX + row * DM + ATT_W + CONV_W + h * 128;
;           mp[ln] = (bf16)f2bf(v0[tt] * rs * nw0 * (g0 * __builtin_amdgcn_rcpf(1.0f + __expf(-g0)))); mp[64 + ln] = (bf16)f2bf(v1[tt] * rs * nw1 * (g1 * __builtin_amdgcn_rcpf(1.0f + __expf(-g1)))); } }
	v_add_f32_e32 v26, v26, v28
	v_xor_b32_e32 v28, 8, v185
	v_cmp_lt_i32_e32 vcc, v28, v27
	s_nop 1
	v_cndmask_b32_e32 v28, v185, v28, vcc
	v_lshlrev_b32_e32 v28, 2, v28
	s_nop 1
	v_mov_b32_dpp v29, v19 row_mirror row_mask:0xf bank_mask:0xf
	s_waitcnt lgkmcnt(0)
	v_add_f32_e32 v19, v19, v29
	s_nop 1
	v_mov_b32_dpp v29, v20 row_mirror row_mask:0xf bank_mask:0xf
	s_waitcnt lgkmcnt(0)
	v_add_f32_e32 v20, v20, v29
	s_nop 1
	v_mov_b32_dpp v29, v21 row_mirror row_mask:0xf bank_mask:0xf
	s_waitcnt lgkmcnt(0)
	v_add_f32_e32 v21, v21, v29
	s_nop 1
	v_mov_b32_dpp v29, v22 row_mirror row_mask:0xf bank_mask:0xf
	s_waitcnt lgkmcnt(0)
	v_add_f32_e32 v22, v22, v29
	s_nop 1
	v_mov_b32_dpp v29, v23 row_mirror row_mask:0xf bank_mask:0xf
	s_waitcnt lgkmcnt(0)
	v_add_f32_e32 v23, v23, v29
	s_nop 1
	v_mov_b32_dpp v29, v24 row_mirror row_mask:0xf bank_mask:0xf
	s_waitcnt lgkmcnt(0)
	v_add_f32_e32 v24, v24, v29
	s_nop 1
	v_mov_b32_dpp v29, v25 row_mirror row_mask:0xf bank_mask:0xf
	s_nop 1
	v_mov_b32_dpp v28, v26 row_mirror row_mask:0xf bank_mask:0xf
	s_waitcnt lgkmcnt(0)
	v_add_f32_e32 v25, v25, v29
	s_waitcnt lgkmcnt(0)
	v_add_f32_e32 v26, v26, v28
	v_xor_b32_e32 v28, 16, v185
	v_cmp_lt_i32_e32 vcc, v28, v27
	s_nop 1
	v_cndmask_b32_e32 v28, v185, v28, vcc
	v_lshlrev_b32_e32 v28, 2, v28
	v_mov_b32_e32 v29, v19
	s_nop 1
	v_permlane16_swap_b32_e32 v19, v29
	s_waitcnt lgkmcnt(0)
	v_add_f32_e32 v19, v19, v29
	v_mov_b32_e32 v29, v20
	s_nop 1
	v_permlane16_swap_b32_e32 v20, v29
	s_waitcnt lgkmcnt(0)
	v_add_f32_e32 v20, v20, v29
	v_mov_b32_e32 v29, v21
	s_nop 1
	v_permlane16_swap_b32_e32 v21, v29
	s_waitcnt lgkmcnt(0)
	v_add_f32_e32 v21, v21, v29
	v_mov_b32_e32 v29, v22
	s_nop 1
	v_permlane16_swap_b32_e32 v22, v29
	s_waitcnt lgkmcnt(0)
	v_add_f32_e32 v22, v22, v29
	v_mov_b32_e32 v29, v23
	s_nop 1
	v_permlane16_swap_b32_e32 v23, v29
	s_waitcnt lgkmcnt(0)
	v_add_f32_e32 v29, v23, v29
	v_mov_b32_e32 v23, v24
	s_nop 1
	v_permlane16_swap_b32_e32 v24, v23
	s_waitcnt lgkmcnt(0)
	v_add_f32_e32 v24, v24, v23
	v_mov_b32_e32 v23, v25
	s_nop 1
	v_permlane16_swap_b32_e32 v25, v23
	s_waitcnt lgkmcnt(0)
	v_add_f32_e32 v25, v25, v23
	v_mov_b32_e32 v23, v26
	s_nop 1
	v_permlane16_swap_b32_e32 v26, v23
	s_waitcnt lgkmcnt(0)
	v_add_f32_e32 v26, v26, v23
	v_xor_b32_e32 v23, 32, v185
	v_cmp_lt_i32_e32 vcc, v23, v27
	s_nop 1
	v_cndmask_b32_e32 v23, v185, v23, vcc
	v_lshlrev_b32_e32 v27, 2, v23
	v_mov_b32_e32 v23, v19
	s_nop 1
	v_permlane32_swap_b32_e32 v19, v23
	s_waitcnt lgkmcnt(0)
	v_add_f32_e32 v28, v19, v23
	v_mov_b32_e32 v19, v20
	s_nop 1
	v_permlane32_swap_b32_e32 v20, v19
	s_waitcnt lgkmcnt(0)
	v_add_f32_e32 v30, v20, v19
	v_mov_b32_e32 v19, v21
	s_nop 1
	v_permlane32_swap_b32_e32 v21, v19
	s_waitcnt lgkmcnt(0)
	v_add_f32_e32 v31, v21, v19
	v_mov_b32_e32 v19, v22
	s_nop 1
	v_permlane32_swap_b32_e32 v22, v19
	s_waitcnt lgkmcnt(0)
	v_add_f32_e32 v23, v22, v19
	v_mov_b32_e32 v19, v29
	s_nop 1
	v_permlane32_swap_b32_e32 v29, v19
	s_waitcnt lgkmcnt(0)
	v_add_f32_e32 v22, v29, v19
	v_mov_b32_e32 v19, v24
	s_nop 1
	v_permlane32_swap_b32_e32 v24, v19
	s_waitcnt lgkmcnt(0)
	v_add_f32_e32 v21, v24, v19
	v_mov_b32_e32 v19, v25
	s_nop 1
	v_permlane32_swap_b32_e32 v25, v19
	v_fmamk_f32 v24, v28, 0x3c000000, v179
	v_cmp_gt_f32_e32 vcc, s12, v24
	s_waitcnt lgkmcnt(0)
	v_add_f32_e32 v20, v25, v19
	v_mul_f32_e32 v25, 0x4f800000, v24
	v_mov_b32_e32 v19, v26
	s_nop 1
	v_permlane32_swap_b32_e32 v26, v19
	v_cndmask_b32_e32 v24, v24, v25, vcc
	v_sqrt_f32_e32 v25, v24
	s_waitcnt lgkmcnt(0)
	v_add_f32_e32 v19, v26, v19
	v_add_u32_e32 v26, -1, v25
	v_fma_f32 v27, -v26, v25, v24
	v_cmp_ge_f32_e64 s[0:1], 0, v27
	v_add_u32_e32 v27, 1, v25
	s_nop 0
	v_cndmask_b32_e64 v26, v25, v26, s[0:1]
	v_fma_f32 v25, -v27, v25, v24
	v_cmp_lt_f32_e64 s[0:1], 0, v25
	s_nop 1
	v_cndmask_b32_e64 v25, v26, v27, s[0:1]
	v_mul_f32_e32 v26, 0x37800000, v25
	v_cndmask_b32_e32 v25, v25, v26, vcc
	v_cmp_class_f32_e32 vcc, v24, v180
	s_nop 1
	v_cndmask_b32_e32 v24, v25, v24, vcc
	v_div_scale_f32 v25, s[0:1], v24, v24, 1.0
	v_rcp_f32_e32 v26, v25
	s_lshl_b64 s[0:1], s[6:7], 12
	s_add_u32 s0, s8, s0
	s_addc_u32 s1, s9, s1
	v_fma_f32 v27, -v25, v26, 1.0
	v_fmac_f32_e32 v26, v27, v26
	v_div_scale_f32 v27, vcc, 1.0, v24, 1.0
	v_mul_f32_e32 v28, v27, v26
	v_fma_f32 v29, -v25, v28, v27
	v_fmac_f32_e32 v28, v29, v26
	v_fma_f32 v25, -v25, v28, v27
	v_div_fmas_f32 v25, v25, v26, v28
	v_div_fixup_f32 v28, v25, v24, 1.0
	v_lshlrev_b32_e32 v24, 16, v227
	v_mul_f32_e32 v25, 0xbfb8aa3b, v24
	v_exp_f32_e32 v25, v25
	v_mul_f32_e32 v16, v16, v28
	s_lshl_b32 s7, s60, 1
	s_waitcnt vmcnt(1)
	v_mul_f32_e32 v16, v18, v16
	v_add_f32_e32 v25, 1.0, v25
	v_rcp_f32_e32 v25, v25
	s_add_u32 s0, s0, s7
	s_addc_u32 s1, s1, 0
	v_lshlrev_b32_e32 v29, 16, v228
	v_mul_f32_e32 v24, v25, v24
	v_mul_f32_e32 v16, v24, v16
	v_bfe_u32 v24, v16, 16, 1
	v_add3_u32 v16, v16, v24, s70
	v_lshl_add_u64 v[24:25], s[0:1], 0, v[146:147]
	v_lshl_add_u64 v[26:27], v[24:25], 0, s[14:15]
	v_add_co_u32_e32 v24, vcc, s10, v24
	s_nop 1
	v_addc_co_u32_e32 v25, vcc, 0, v25, vcc
	global_store_short_d16_hi v[24:25], v16, off offset:3072
	v_mul_f32_e32 v16, v17, v28
	v_mul_f32_e32 v17, 0xbfb8aa3b, v29
	v_exp_f32_e32 v17, v17
	s_waitcnt vmcnt(1)
; __device__ __forceinline__ unsigned f2bf(float f) { unsigned u = __builtin_bit_cast(unsigned, f); return (u + 0x7fffu + ((u >> 16) & 1u)) >> 16; }
; __device__ __forceinline__ void hg_h3_unit(Frame& F, int l, int unit) {
;     ...
;       for (int tt = 0; tt < 8; ++tt) { const int t = F.wave * 8 + tt; const float rs = 1.0f / sqrtf(ss[tt] * (1.0f / 128.0f) + LN_EPS);
;           const size_t row = (size_t)(base0 + t); const float g0 = bflo(gin0[tt]), g1 = bflo(gin1[tt]);
;           bf16* mp = MIX + row * DM + ATT_W + CONV_W + h * 128;
;           mp[ln] = (bf16)f2bf(v0[tt] * rs * nw0 * (g0 * __builtin_amdgcn_rcpf(1.0f + __expf(-g0)))); mp[64 + ln] = (bf16)f2bf(v1[tt] * rs * nw1 * (g1 * __builtin_amdgcn_rcpf(1.0f + __expf(-g1)))); } }
	v_mul_f32_e32 v16, v1, v16
	v_add_f32_e32 v17, 1.0, v17
	v_rcp_f32_e32 v17, v17
	s_nop 0
	v_mul_f32_e32 v17, v17, v29
	v_mul_f32_e32 v16, v17, v16
	v_bfe_u32 v17, v16, 16, 1
	v_add3_u32 v16, v16, v17, s70
	global_store_short_d16_hi v[26:27], v16, off offset:128
	v_fmamk_f32 v16, v30, 0x3c000000, v179
	v_cmp_gt_f32_e32 vcc, s12, v16
	v_mul_f32_e32 v17, 0x4f800000, v16
	s_nop 0
	v_cndmask_b32_e32 v16, v16, v17, vcc
	v_sqrt_f32_e32 v17, v16
	s_nop 0
	v_add_u32_e32 v24, -1, v17
	v_fma_f32 v25, -v24, v17, v16
	v_cmp_ge_f32_e64 s[0:1], 0, v25
	v_add_u32_e32 v25, 1, v17
	s_nop 0
	v_cndmask_b32_e64 v24, v17, v24, s[0:1]
	v_fma_f32 v17, -v25, v17, v16
	v_cmp_lt_f32_e64 s[0:1], 0, v17
	s_nop 1
	v_cndmask_b32_e64 v17, v24, v25, s[0:1]
	v_mul_f32_e32 v24, 0x37800000, v17
	v_cndmask_b32_e32 v17, v17, v24, vcc
	v_cmp_class_f32_e32 vcc, v16, v180
	s_nop 1
	v_cndmask_b32_e32 v16, v17, v16, vcc
	v_div_scale_f32 v17, s[0:1], v16, v16, 1.0
	v_rcp_f32_e32 v24, v17
	s_or_b32 s0, s6, 1
	s_ashr_i32 s1, s0, 31
	s_lshl_b64 s[0:1], s[0:1], 12
	v_fma_f32 v25, -v17, v24, 1.0
	v_fmac_f32_e32 v24, v25, v24
	v_div_scale_f32 v25, vcc, 1.0, v16, 1.0
	v_mul_f32_e32 v26, v25, v24
	v_fma_f32 v27, -v17, v26, v25
	v_fmac_f32_e32 v26, v27, v24
	v_fma_f32 v17, -v17, v26, v25
	v_div_fmas_f32 v17, v17, v24, v26
	v_div_fixup_f32 v26, v17, v16, 1.0
	v_lshlrev_b32_e32 v16, 16, v225
	v_mul_f32_e32 v17, 0xbfb8aa3b, v16
	v_exp_f32_e32 v17, v17
	s_add_u32 s0, s8, s0
	v_mul_f32_e32 v14, v14, v26
	s_addc_u32 s1, s9, s1
	v_add_f32_e32 v17, 1.0, v17
	v_rcp_f32_e32 v17, v17
	v_mul_f32_e32 v14, v18, v14
	s_add_u32 s0, s0, s7
	s_addc_u32 s1, s1, 0
	v_mul_f32_e32 v16, v17, v16
	v_mul_f32_e32 v14, v16, v14
	v_bfe_u32 v16, v14, 16, 1
	v_add3_u32 v14, v14, v16, s70
	v_lshl_add_u64 v[16:17], s[0:1], 0, v[146:147]
	v_lshl_add_u64 v[24:25], v[16:17], 0, s[14:15]
	v_add_co_u32_e32 v16, vcc, s10, v16
	v_lshlrev_b32_e32 v27, 16, v226
	s_nop 0
	v_addc_co_u32_e32 v17, vcc, 0, v17, vcc
	global_store_short_d16_hi v[16:17], v14, off offset:3072
	v_mul_f32_e32 v14, v15, v26
	v_mul_f32_e32 v15, 0xbfb8aa3b, v27
	v_exp_f32_e32 v15, v15
	v_mul_f32_e32 v14, v1, v14
	v_add_f32_e32 v15, 1.0, v15
	v_rcp_f32_e32 v15, v15
	s_nop 0
	v_mul_f32_e32 v15, v15, v27
	v_mul_f32_e32 v14, v15, v14
	v_bfe_u32 v15, v14, 16, 1
	v_add3_u32 v14, v14, v15, s70
	global_store_short_d16_hi v[24:25], v14, off offset:128
	v_fmamk_f32 v14, v31, 0x3c000000, v179
	v_cmp_gt_f32_e32 vcc, s12, v14
	v_mul_f32_e32 v15, 0x4f800000, v14
	s_nop 0
	v_cndmask_b32_e32 v14, v14, v15, vcc
	v_sqrt_f32_e32 v15, v14
	s_nop 0
	v_add_u32_e32 v16, -1, v15
	v_fma_f32 v17, -v16, v15, v14
	v_cmp_ge_f32_e64 s[0:1], 0, v17
	v_add_u32_e32 v17, 1, v15
	s_nop 0
	v_cndmask_b32_e64 v16, v15, v16, s[0:1]
	v_fma_f32 v15, -v17, v15, v14
	v_cmp_lt_f32_e64 s[0:1], 0, v15
	s_nop 1
	v_cndmask_b32_e64 v15, v16, v17, s[0:1]
	v_mul_f32_e32 v16, 0x37800000, v15
	v_cndmask_b32_e32 v15, v15, v16, vcc
	v_cmp_class_f32_e32 vcc, v14, v180
	s_nop 1
	v_cndmask_b32_e32 v14, v15, v14, vcc
	v_div_scale_f32 v15, s[0:1], v14, v14, 1.0
	v_rcp_f32_e32 v16, v15
	s_or_b32 s0, s6, 2
	s_ashr_i32 s1, s0, 31
	s_lshl_b64 s[0:1], s[0:1], 12
	v_fma_f32 v17, -v15, v16, 1.0
	v_fmac_f32_e32 v16, v17, v16
	v_div_scale_f32 v17, vcc, 1.0, v14, 1.0
	v_mul_f32_e32 v24, v17, v16
	v_fma_f32 v25, -v15, v24, v17
	v_fmac_f32_e32 v24, v25, v16
	v_fma_f32 v15, -v15, v24, v17
	v_div_fmas_f32 v15, v15, v16, v24
	v_div_fixup_f32 v24, v15, v14, 1.0
	v_lshlrev_b32_e32 v14, 16, v223
	v_mul_f32_e32 v15, 0xbfb8aa3b, v14
	v_exp_f32_e32 v15, v15
	s_add_u32 s0, s8, s0
	v_mul_f32_e32 v12, v12, v24
	s_addc_u32 s1, s9, s1
	v_add_f32_e32 v15, 1.0, v15
	v_rcp_f32_e32 v15, v15
	v_mul_f32_e32 v12, v18, v12
	s_add_u32 s0, s0, s7
	s_addc_u32 s1, s1, 0
	v_mul_f32_e32 v14, v15, v14
	v_mul_f32_e32 v12, v14, v12
	v_bfe_u32 v14, v12, 16, 1
	v_add3_u32 v12, v12, v14, s70
	v_lshl_add_u64 v[14:15], s[0:1], 0, v[146:147]
	v_lshl_add_u64 v[16:17], v[14:15], 0, s[14:15]
	v_add_co_u32_e32 v14, vcc, s10, v14
	v_lshlrev_b32_e32 v25, 16, v224
	s_nop 0
	v_addc_co_u32_e32 v15, vcc, 0, v15, vcc
	global_store_short_d16_hi v[14:15], v12, off offset:3072
	v_mul_f32_e32 v12, v13, v24
	v_mul_f32_e32 v13, 0xbfb8aa3b, v25
	v_exp_f32_e32 v13, v13
	v_mul_f32_e32 v12, v1, v12
	v_add_f32_e32 v13, 1.0, v13
	v_rcp_f32_e32 v13, v13
	s_nop 0
	v_mul_f32_e32 v13, v13, v25
	v_mul_f32_e32 v12, v13, v12
	v_bfe_u32 v13, v12, 16, 1
	v_add3_u32 v12, v12, v13, s70
	global_store_short_d16_hi v[16:17], v12, off offset:128
	v_fmamk_f32 v12, v23, 0x3c000000, v179
	v_cmp_gt_f32_e32 vcc, s12, v12
	v_mul_f32_e32 v13, 0x4f800000, v12
	s_nop 0
	v_cndmask_b32_e32 v12, v12, v13, vcc
	v_sqrt_f32_e32 v13, v12
	s_nop 0
	v_add_u32_e32 v14, -1, v13
	v_fma_f32 v15, -v14, v13, v12
	v_cmp_ge_f32_e64 s[0:1], 0, v15
	v_add_u32_e32 v15, 1, v13
	s_nop 0
	v_cndmask_b32_e64 v14, v13, v14, s[0:1]
	v_fma_f32 v13, -v15, v13, v12
	v_cmp_lt_f32_e64 s[0:1], 0, v13
	s_nop 1
	v_cndmask_b32_e64 v13, v14, v15, s[0:1]
	v_mul_f32_e32 v14, 0x37800000, v13
	v_cndmask_b32_e32 v13, v13, v14, vcc
	v_cmp_class_f32_e32 vcc, v12, v180
	s_nop 1
	v_cndmask_b32_e32 v12, v13, v12, vcc
	v_div_scale_f32 v13, s[0:1], v12, v12, 1.0
	v_rcp_f32_e32 v14, v13
	s_or_b32 s0, s6, 3
	s_ashr_i32 s1, s0, 31
	s_lshl_b64 s[0:1], s[0:1], 12
	v_fma_f32 v15, -v13, v14, 1.0
	v_fmac_f32_e32 v14, v15, v14
	v_div_scale_f32 v15, vcc, 1.0, v12, 1.0
	v_mul_f32_e32 v16, v15, v14
	v_fma_f32 v17, -v13, v16, v15
	v_fmac_f32_e32 v16, v17, v14
	v_fma_f32 v13, -v13, v16, v15
	v_div_fmas_f32 v13, v13, v14, v16
	v_div_fixup_f32 v16, v13, v12, 1.0
	v_lshlrev_b32_e32 v12, 16, v221
	v_mul_f32_e32 v13, 0xbfb8aa3b, v12
	v_exp_f32_e32 v13, v13
	s_add_u32 s0, s8, s0
; __device__ __forceinline__ unsigned f2bf(float f) { unsigned u = __builtin_bit_cast(unsigned, f); return (u + 0x7fffu + ((u >> 16) & 1u)) >> 16; }
; __device__ __forceinline__ void hg_h3_unit(Frame& F, int l, int unit) {
;     ...
;       for (int tt = 0; tt < 8; ++tt) { const int t = F.wave * 8 + tt; const float rs = 1.0f / sqrtf(ss[tt] * (1.0f / 128.0f) + LN_EPS);
;           const size_t row = (size_t)(base0 + t); const float g0 = bflo(gin0[tt]), g1 = bflo(gin1[tt]);
;           bf16* mp = MIX + row * DM + ATT_W + CONV_W + h * 128;
;           mp[ln] = (bf16)f2bf(v0[tt] * rs * nw0 * (g0 * __builtin_amdgcn_rcpf(1.0f + __expf(-g0)))); mp[64 + ln] = (bf16)f2bf(v1[tt] * rs * nw1 * (g1 * __builtin_amdgcn_rcpf(1.0f + __expf(-g1)))); } }
	v_mul_f32_e32 v10, v10, v16
	s_addc_u32 s1, s9, s1
	v_add_f32_e32 v13, 1.0, v13
	v_rcp_f32_e32 v13, v13
	v_mul_f32_e32 v10, v18, v10
	s_add_u32 s0, s0, s7
	s_addc_u32 s1, s1, 0
	v_mul_f32_e32 v12, v13, v12
	v_mul_f32_e32 v10, v12, v10
	v_bfe_u32 v12, v10, 16, 1
	v_add3_u32 v10, v10, v12, s70
	v_lshl_add_u64 v[12:13], s[0:1], 0, v[146:147]
	v_lshl_add_u64 v[14:15], v[12:13], 0, s[14:15]
	v_add_co_u32_e32 v12, vcc, s10, v12
	v_lshlrev_b32_e32 v17, 16, v222
	s_nop 0
	v_addc_co_u32_e32 v13, vcc, 0, v13, vcc
	global_store_short_d16_hi v[12:13], v10, off offset:3072
	v_mul_f32_e32 v10, v11, v16
	v_mul_f32_e32 v11, 0xbfb8aa3b, v17
	v_exp_f32_e32 v11, v11
	v_mul_f32_e32 v10, v1, v10
	v_add_f32_e32 v11, 1.0, v11
	v_rcp_f32_e32 v11, v11
	s_nop 0
	v_mul_f32_e32 v11, v11, v17
	v_mul_f32_e32 v10, v11, v10
	v_bfe_u32 v11, v10, 16, 1
	v_add3_u32 v10, v10, v11, s70
	global_store_short_d16_hi v[14:15], v10, off offset:128
	v_fmamk_f32 v10, v22, 0x3c000000, v179
	v_cmp_gt_f32_e32 vcc, s12, v10
	v_mul_f32_e32 v11, 0x4f800000, v10
	s_nop 0
	v_cndmask_b32_e32 v10, v10, v11, vcc
	v_sqrt_f32_e32 v11, v10
	s_nop 0
	v_add_u32_e32 v12, -1, v11
	v_fma_f32 v13, -v12, v11, v10
	v_cmp_ge_f32_e64 s[0:1], 0, v13
	v_add_u32_e32 v13, 1, v11
	s_nop 0
	v_cndmask_b32_e64 v12, v11, v12, s[0:1]
	v_fma_f32 v11, -v13, v11, v10
	v_cmp_lt_f32_e64 s[0:1], 0, v11
	s_nop 1
	v_cndmask_b32_e64 v11, v12, v13, s[0:1]
	v_mul_f32_e32 v12, 0x37800000, v11
	v_cndmask_b32_e32 v11, v11, v12, vcc
	v_cmp_class_f32_e32 vcc, v10, v180
	s_nop 1
	v_cndmask_b32_e32 v10, v11, v10, vcc
	v_div_scale_f32 v11, s[0:1], v10, v10, 1.0
	v_rcp_f32_e32 v12, v11
	s_or_b32 s0, s6, 4
	s_ashr_i32 s1, s0, 31
	s_lshl_b64 s[0:1], s[0:1], 12
	v_fma_f32 v13, -v11, v12, 1.0
	v_fmac_f32_e32 v12, v13, v12
	v_div_scale_f32 v13, vcc, 1.0, v10, 1.0
	v_mul_f32_e32 v14, v13, v12
	v_fma_f32 v15, -v11, v14, v13
	v_fmac_f32_e32 v14, v15, v12
	v_fma_f32 v11, -v11, v14, v13
	v_div_fmas_f32 v11, v11, v12, v14
	v_div_fixup_f32 v14, v11, v10, 1.0
	v_lshlrev_b32_e32 v10, 16, v219
	v_mul_f32_e32 v11, 0xbfb8aa3b, v10
	v_exp_f32_e32 v11, v11
	s_add_u32 s0, s8, s0
	v_mul_f32_e32 v8, v8, v14
	s_addc_u32 s1, s9, s1
	v_add_f32_e32 v11, 1.0, v11
	v_rcp_f32_e32 v11, v11
	v_mul_f32_e32 v8, v18, v8
	s_add_u32 s0, s0, s7
	s_addc_u32 s1, s1, 0
	v_mul_f32_e32 v10, v11, v10
	v_mul_f32_e32 v8, v10, v8
	v_bfe_u32 v10, v8, 16, 1
	v_add3_u32 v8, v8, v10, s70
	v_lshl_add_u64 v[10:11], s[0:1], 0, v[146:147]
	v_lshl_add_u64 v[12:13], v[10:11], 0, s[14:15]
	v_add_co_u32_e32 v10, vcc, s10, v10
	v_lshlrev_b32_e32 v15, 16, v220
	s_nop 0
	v_addc_co_u32_e32 v11, vcc, 0, v11, vcc
	global_store_short_d16_hi v[10:11], v8, off offset:3072
	v_mul_f32_e32 v8, v9, v14
	v_mul_f32_e32 v9, 0xbfb8aa3b, v15
	v_exp_f32_e32 v9, v9
	v_mul_f32_e32 v8, v1, v8
	v_add_f32_e32 v9, 1.0, v9
	v_rcp_f32_e32 v9, v9
	s_nop 0
	v_mul_f32_e32 v9, v9, v15
	v_mul_f32_e32 v8, v9, v8
	v_bfe_u32 v9, v8, 16, 1
	v_add3_u32 v8, v8, v9, s70
	global_store_short_d16_hi v[12:13], v8, off offset:128
	v_fmamk_f32 v8, v21, 0x3c000000, v179
	v_cmp_gt_f32_e32 vcc, s12, v8
	v_mul_f32_e32 v9, 0x4f800000, v8
	s_nop 0
	v_cndmask_b32_e32 v8, v8, v9, vcc
	v_sqrt_f32_e32 v9, v8
	s_nop 0
	v_add_u32_e32 v10, -1, v9
	v_fma_f32 v11, -v10, v9, v8
	v_cmp_ge_f32_e64 s[0:1], 0, v11
	v_add_u32_e32 v11, 1, v9
	s_nop 0
	v_cndmask_b32_e64 v10, v9, v10, s[0:1]
	v_fma_f32 v9, -v11, v9, v8
	v_cmp_lt_f32_e64 s[0:1], 0, v9
	s_nop 1
	v_cndmask_b32_e64 v9, v10, v11, s[0:1]
	v_mul_f32_e32 v10, 0x37800000, v9
	v_cndmask_b32_e32 v9, v9, v10, vcc
	v_cmp_class_f32_e32 vcc, v8, v180
	s_nop 1
	v_cndmask_b32_e32 v8, v9, v8, vcc
	v_div_scale_f32 v9, s[0:1], v8, v8, 1.0
	v_rcp_f32_e32 v10, v9
	s_or_b32 s0, s6, 5
	s_ashr_i32 s1, s0, 31
	s_lshl_b64 s[0:1], s[0:1], 12
	v_fma_f32 v11, -v9, v10, 1.0
	v_fmac_f32_e32 v10, v11, v10
	v_div_scale_f32 v11, vcc, 1.0, v8, 1.0
	v_mul_f32_e32 v12, v11, v10
	v_fma_f32 v13, -v9, v12, v11
	v_fmac_f32_e32 v12, v13, v10
	v_fma_f32 v9, -v9, v12, v11
	v_div_fmas_f32 v9, v9, v10, v12
	v_div_fixup_f32 v12, v9, v8, 1.0
	v_lshlrev_b32_e32 v8, 16, v217
	v_mul_f32_e32 v9, 0xbfb8aa3b, v8
	v_exp_f32_e32 v9, v9
	s_add_u32 s0, s8, s0
	v_mul_f32_e32 v6, v6, v12
	s_addc_u32 s1, s9, s1
	v_add_f32_e32 v9, 1.0, v9
	v_rcp_f32_e32 v9, v9
	v_mul_f32_e32 v6, v18, v6
	s_add_u32 s0, s0, s7
	s_addc_u32 s1, s1, 0
	v_mul_f32_e32 v8, v9, v8
	v_mul_f32_e32 v6, v8, v6
	v_bfe_u32 v8, v6, 16, 1
	v_add3_u32 v6, v6, v8, s70
	v_lshl_add_u64 v[8:9], s[0:1], 0, v[146:147]
	v_lshl_add_u64 v[10:11], v[8:9], 0, s[14:15]
; #define LDS_BARRIER() asm volatile("s_waitcnt lgkmcnt(0)\n\ts_barrier" ::: "memory")
; __device__ __forceinline__ unsigned f2bf(float f) { unsigned u = __builtin_bit_cast(unsigned, f); return (u + 0x7fffu + ((u >> 16) & 1u)) >> 16; }
; #define H3SEG(k) do { if (MK_HSEL >= 0 && blockIdx.x == 0 && threadIdx.x == 0) { volatile LAS unsigned* hs_ = (volatile LAS unsigned*)(F.lds + RING_BYTES + 128); const unsigned tn_ = (unsigned)__builtin_amdgcn_s_memrealtime(); if (MK_HSEL == (k)) hs_[0] += tn_ - hs_[1]; hs_[1] = tn_; } } while (0)
; __device__ __forceinline__ void hg_h3_unit(Frame& F, int l, int unit) {
;     ...
;       for (int tt = 0; tt < 8; ++tt) { const int t = F.wave * 8 + tt; const float rs = 1.0f / sqrtf(ss[tt] * (1.0f / 128.0f) + LN_EPS);
;           const size_t row = (size_t)(base0 + t); const float g0 = bflo(gin0[tt]), g1 = bflo(gin1[tt]);
;           bf16* mp = MIX + row * DM + ATT_W + CONV_W + h * 128;
;           mp[ln] = (bf16)f2bf(v0[tt] * rs * nw0 * (g0 * __builtin_amdgcn_rcpf(1.0f + __expf(-g0)))); mp[64 + ln] = (bf16)f2bf(v1[tt] * rs * nw1 * (g1 * __builtin_amdgcn_rcpf(1.0f + __expf(-g1)))); } }
;     LDS_BARRIER(); H3SEG(3);
	v_add_co_u32_e32 v8, vcc, s10, v8
	v_lshlrev_b32_e32 v13, 16, v218
	s_nop 0
	v_addc_co_u32_e32 v9, vcc, 0, v9, vcc
	global_store_short_d16_hi v[8:9], v6, off offset:3072
	v_mul_f32_e32 v6, v7, v12
	v_mul_f32_e32 v7, 0xbfb8aa3b, v13
	v_exp_f32_e32 v7, v7
	v_mul_f32_e32 v6, v1, v6
	v_add_f32_e32 v7, 1.0, v7
	v_rcp_f32_e32 v7, v7
	s_nop 0
	v_mul_f32_e32 v7, v7, v13
	v_mul_f32_e32 v6, v7, v6
	v_bfe_u32 v7, v6, 16, 1
	v_add3_u32 v6, v6, v7, s70
	global_store_short_d16_hi v[10:11], v6, off offset:128
	v_fmamk_f32 v6, v20, 0x3c000000, v179
	v_cmp_gt_f32_e32 vcc, s12, v6
	v_mul_f32_e32 v7, 0x4f800000, v6
	s_nop 0
	v_cndmask_b32_e32 v6, v6, v7, vcc
	v_sqrt_f32_e32 v7, v6
	s_nop 0
	v_add_u32_e32 v8, -1, v7
	v_fma_f32 v9, -v8, v7, v6
	v_cmp_ge_f32_e64 s[0:1], 0, v9
	v_add_u32_e32 v9, 1, v7
	s_nop 0
	v_cndmask_b32_e64 v8, v7, v8, s[0:1]
	v_fma_f32 v7, -v9, v7, v6
	v_cmp_lt_f32_e64 s[0:1], 0, v7
	s_nop 1
	v_cndmask_b32_e64 v7, v8, v9, s[0:1]
	v_mul_f32_e32 v8, 0x37800000, v7
	v_cndmask_b32_e32 v7, v7, v8, vcc
	v_cmp_class_f32_e32 vcc, v6, v180
	s_nop 1
	v_cndmask_b32_e32 v6, v7, v6, vcc
	v_div_scale_f32 v7, s[0:1], v6, v6, 1.0
	v_rcp_f32_e32 v8, v7
	s_or_b32 s0, s6, 6
	s_ashr_i32 s1, s0, 31
	s_lshl_b64 s[0:1], s[0:1], 12
	v_fma_f32 v9, -v7, v8, 1.0
	v_fmac_f32_e32 v8, v9, v8
	v_div_scale_f32 v9, vcc, 1.0, v6, 1.0
	v_mul_f32_e32 v10, v9, v8
	v_fma_f32 v11, -v7, v10, v9
	v_fmac_f32_e32 v10, v11, v8
	v_fma_f32 v7, -v7, v10, v9
	v_div_fmas_f32 v7, v7, v8, v10
	v_div_fixup_f32 v10, v7, v6, 1.0
	v_lshlrev_b32_e32 v6, 16, v215
	v_mul_f32_e32 v7, 0xbfb8aa3b, v6
	v_exp_f32_e32 v7, v7
	s_add_u32 s0, s8, s0
	v_mul_f32_e32 v4, v4, v10
	s_addc_u32 s1, s9, s1
	v_add_f32_e32 v7, 1.0, v7
	v_rcp_f32_e32 v7, v7
	v_mul_f32_e32 v4, v18, v4
	s_add_u32 s0, s0, s7
	s_addc_u32 s1, s1, 0
	v_mul_f32_e32 v6, v7, v6
	v_mul_f32_e32 v4, v6, v4
	v_bfe_u32 v6, v4, 16, 1
	v_add3_u32 v4, v4, v6, s70
	v_lshl_add_u64 v[6:7], s[0:1], 0, v[146:147]
	v_lshl_add_u64 v[8:9], v[6:7], 0, s[14:15]
	v_add_co_u32_e32 v6, vcc, s10, v6
	v_lshlrev_b32_e32 v11, 16, v216
	s_nop 0
	v_addc_co_u32_e32 v7, vcc, 0, v7, vcc
	global_store_short_d16_hi v[6:7], v4, off offset:3072
	v_mul_f32_e32 v4, v5, v10
	v_mul_f32_e32 v5, 0xbfb8aa3b, v11
	v_exp_f32_e32 v5, v5
	v_mul_f32_e32 v4, v1, v4
	v_add_f32_e32 v5, 1.0, v5
	v_rcp_f32_e32 v5, v5
	s_nop 0
	v_mul_f32_e32 v5, v5, v11
	v_mul_f32_e32 v4, v5, v4
	v_bfe_u32 v5, v4, 16, 1
	v_add3_u32 v4, v4, v5, s70
	global_store_short_d16_hi v[8:9], v4, off offset:128
	v_fmamk_f32 v4, v19, 0x3c000000, v179
	v_cmp_gt_f32_e32 vcc, s12, v4
	v_mul_f32_e32 v5, 0x4f800000, v4
	s_nop 0
	v_cndmask_b32_e32 v4, v4, v5, vcc
	v_sqrt_f32_e32 v5, v4
	s_nop 0
	v_add_u32_e32 v6, -1, v5
	v_fma_f32 v7, -v6, v5, v4
	v_cmp_ge_f32_e64 s[0:1], 0, v7
	v_add_u32_e32 v7, 1, v5
	s_nop 0
	v_cndmask_b32_e64 v6, v5, v6, s[0:1]
	v_fma_f32 v5, -v7, v5, v4
	v_cmp_lt_f32_e64 s[0:1], 0, v5
	s_nop 1
	v_cndmask_b32_e64 v5, v6, v7, s[0:1]
	v_mul_f32_e32 v6, 0x37800000, v5
	v_cndmask_b32_e32 v5, v5, v6, vcc
	v_cmp_class_f32_e32 vcc, v4, v180
	s_nop 1
	v_cndmask_b32_e32 v4, v5, v4, vcc
	v_div_scale_f32 v5, s[0:1], v4, v4, 1.0
	v_rcp_f32_e32 v6, v5
	s_or_b32 s0, s6, 7
	s_ashr_i32 s1, s0, 31
	s_lshl_b64 s[0:1], s[0:1], 12
	v_fma_f32 v7, -v5, v6, 1.0
	v_fmac_f32_e32 v6, v7, v6
	v_div_scale_f32 v7, vcc, 1.0, v4, 1.0
	v_mul_f32_e32 v8, v7, v6
	v_fma_f32 v9, -v5, v8, v7
	v_fmac_f32_e32 v8, v9, v6
	v_fma_f32 v5, -v5, v8, v7
	v_div_fmas_f32 v5, v5, v6, v8
	v_div_fixup_f32 v8, v5, v4, 1.0
	v_lshlrev_b32_e32 v4, 16, v213
	v_mul_f32_e32 v5, 0xbfb8aa3b, v4
	v_exp_f32_e32 v5, v5
	s_add_u32 s0, s8, s0
	v_mul_f32_e32 v2, v2, v8
	s_addc_u32 s1, s9, s1
	v_add_f32_e32 v5, 1.0, v5
	v_rcp_f32_e32 v5, v5
	v_mul_f32_e32 v2, v18, v2
	s_add_u32 s0, s0, s7
	s_addc_u32 s1, s1, 0
	v_mul_f32_e32 v4, v5, v4
	v_mul_f32_e32 v2, v4, v2
	v_bfe_u32 v4, v2, 16, 1
	v_add3_u32 v2, v2, v4, s70
	v_lshl_add_u64 v[4:5], s[0:1], 0, v[146:147]
	v_lshl_add_u64 v[6:7], v[4:5], 0, s[14:15]
	v_add_co_u32_e32 v4, vcc, s10, v4
	v_lshlrev_b32_e32 v9, 16, v214
	s_nop 0
	v_addc_co_u32_e32 v5, vcc, 0, v5, vcc
	global_store_short_d16_hi v[4:5], v2, off offset:3072
	v_mul_f32_e32 v2, v3, v8
	v_mul_f32_e32 v1, v1, v2
	v_mul_f32_e32 v2, 0xbfb8aa3b, v9
	v_exp_f32_e32 v2, v2
	s_mov_b64 s[0:1], 0
	v_add_f32_e32 v2, 1.0, v2
	v_rcp_f32_e32 v2, v2
	s_nop 0
	v_mul_f32_e32 v2, v2, v9
	v_mul_f32_e32 v1, v2, v1
	v_bfe_u32 v2, v1, 16, 1
	v_add3_u32 v1, v1, v2, s70
	global_store_short_d16_hi v[6:7], v1, off offset:128
	s_waitcnt lgkmcnt(0)
	s_barrier
